# f33 + GLA chunk-increment unit: 64 two-byte stores per lane paired into 32 four-byte stores (neighbour bf16 via DPP, rows i and i+1 share one store)
# baseline (speedup 1.0000x reference)
; __device__ __forceinline__ unsigned pk2(float lo, float hi) { f32x2 v = {lo, hi}; bf16x2_t b = __builtin_convertvector(v, bf16x2_t); return __builtin_bit_cast(unsigned, b); }
; __device__ __forceinline__ int crow(int r, int hi) { return (r & 3) + 8 * (r >> 2) + 4 * hi; }
; #define MFMA32(a, b, c) __builtin_amdgcn_mfma_f32_32x32x16_bf16((a), (b), (c), 0, 0, 0)
; __device__ __forceinline__ void gla_inc_unit(Frame& F, int bh, int n) {
;     ...
;     f32x16 acc[4];
; #pragma unroll
;     for (int c = 0; c < 4; ++c)
; #pragma unroll
;         for (int i = 0; i < 16; ++i) acc[c][i] = 0.f;
; #pragma unroll
;     for (int s = 0; s < 4; ++s) {
;         const bf16x8 af = trfrag(lds + GL_VT + (16 * s + 8 * h + q4) * VST + (32 * wid + 16 * b16 + 4 * p4) * 2, 4 * VST);
; #pragma unroll
;         for (int c = 0; c < 4; ++c) { const bf16x8 bf = trfrag(lds + GL_KT + (16 * s + 8 * h + q4) * 320 + (32 * c + 16 * b16 + 4 * p4) * 2, 4 * 320); acc[c] = MFMA32(af, bf, acc[c]); }
;     }
;     bf16* sb = WSP(bf16, WS_SB) + (size_t)(bh * 64 + n) * 256 * 128;
; #pragma unroll
;     for (int c = 0; c < 4; ++c)
; #pragma unroll
;         for (int i = 0; i < 16; ++i) sb[(size_t)(32 * wid + crow(i, h)) * 128 + 32 * c + (lane & 31)] = (bf16)(pk2(acc[c][i], 0.f) & 0xffffu);
.LBB0_636:
	s_or_b64 exec, exec, s[16:17]
	v_bfe_u32 v2, v68, 2, 2
	v_bfe_u32 v66, v68, 5, 1
	v_and_b32_e32 v3, 16, v68
	v_lshl_or_b32 v6, v66, 3, v2
	v_and_b32_e32 v2, 12, v12
	v_or3_b32 v4, v3, s18, v2
	v_or_b32_e32 v2, v2, v3
	v_lshlrev_b32_e32 v4, 1, v4
	v_lshlrev_b32_e32 v7, 1, v2
	v_mul_u32_u24_e32 v2, 0x240, v6
	v_add3_u32 v69, 0, v4, v2
	s_waitcnt lgkmcnt(0)
	s_barrier
	ds_read_b64_tr_b16 v[2:3], v69 offset:32768
	ds_read_b64_tr_b16 v[4:5], v69 offset:35072
	v_mul_u32_u24_e32 v6, 0x140, v6
	v_add3_u32 v118, s24, v6, v7
	ds_read_b64_tr_b16 v[6:7], v118
	ds_read_b64_tr_b16 v[10:11], v118 offset:64
	ds_read_b64_tr_b16 v[14:15], v118 offset:128
	ds_read_b64_tr_b16 v[72:73], v118 offset:192
	ds_read_b64_tr_b16 v[8:9], v118 offset:1280
	ds_read_b64_tr_b16 v[12:13], v118 offset:1344
	ds_read_b64_tr_b16 v[16:17], v118 offset:1408
	ds_read_b64_tr_b16 v[74:75], v118 offset:1472
	ds_read_b64_tr_b16 v[76:77], v69 offset:41984
	ds_read_b64_tr_b16 v[78:79], v69 offset:44288
	s_waitcnt lgkmcnt(5)
	v_mfma_f32_32x32x16_bf16 v[50:65], v[2:5], v[6:9], 0
	v_lshlrev_b64 v[70:71], 16, v[70:71]
	v_lshl_add_u64 v[70:71], s[4:5], 0, v[70:71]
	s_add_u32 s10, s10, s14
	s_addc_u32 s11, s11, s15
	s_add_u32 s6, s6, s8
	s_addc_u32 s7, s7, s9
	s_add_i32 s19, s19, s20
	s_waitcnt lgkmcnt(4)
	v_mfma_f32_32x32x16_bf16 v[34:49], v[2:5], v[10:13], 0
	s_cmpk_gt_i32 s10, 0x1ff
	s_waitcnt lgkmcnt(3)
	v_mfma_f32_32x32x16_bf16 v[18:33], v[2:5], v[14:17], 0
	s_waitcnt lgkmcnt(2)
	v_mfma_f32_32x32x16_bf16 v[2:17], v[2:5], v[72:75], 0
	ds_read_b64_tr_b16 v[74:75], v118 offset:6400
	ds_read_b64_tr_b16 v[72:73], v118 offset:5120
	ds_read_b64_tr_b16 v[80:81], v118 offset:5184
	ds_read_b64_tr_b16 v[84:85], v118 offset:5248
	ds_read_b64_tr_b16 v[88:89], v118 offset:5312
	ds_read_b64_tr_b16 v[82:83], v118 offset:6464
	ds_read_b64_tr_b16 v[86:87], v118 offset:6528
	ds_read_b64_tr_b16 v[90:91], v118 offset:6592
	s_waitcnt lgkmcnt(6)
	v_mfma_f32_32x32x16_bf16 v[50:65], v[76:79], v[72:75], v[50:65]
	s_waitcnt lgkmcnt(2)
	v_mfma_f32_32x32x16_bf16 v[34:49], v[76:79], v[80:83], v[34:49]
	ds_read_b64_tr_b16 v[72:73], v69 offset:51200
	ds_read_b64_tr_b16 v[74:75], v69 offset:53504
	ds_read_b64_tr_b16 v[80:81], v118 offset:10240
	ds_read_b64_tr_b16 v[92:93], v118 offset:10304
	ds_read_b64_tr_b16 v[96:97], v118 offset:10368
	ds_read_b64_tr_b16 v[100:101], v118 offset:10432
	s_waitcnt lgkmcnt(7)
	v_mfma_f32_32x32x16_bf16 v[18:33], v[76:79], v[84:87], v[18:33]
	ds_read_b64_tr_b16 v[82:83], v118 offset:11520
	ds_read_b64_tr_b16 v[94:95], v118 offset:11584
	ds_read_b64_tr_b16 v[98:99], v118 offset:11648
	ds_read_b64_tr_b16 v[102:103], v118 offset:11712
	ds_read_b64_tr_b16 v[84:85], v69 offset:60416
	ds_read_b64_tr_b16 v[86:87], v69 offset:62720
	ds_read_b64_tr_b16 v[104:105], v118 offset:15360
	ds_read_b64_tr_b16 v[108:109], v118 offset:15424
	ds_read_b64_tr_b16 v[112:113], v118 offset:15488
	ds_read_b64_tr_b16 v[116:117], v118 offset:15552
	ds_read_b64_tr_b16 v[106:107], v118 offset:16640
	ds_read_b64_tr_b16 v[110:111], v118 offset:16704
	ds_read_b64_tr_b16 v[114:115], v118 offset:16768
	ds_read_b64_tr_b16 v[118:119], v118 offset:16832
	s_waitcnt lgkmcnt(13)
	v_mfma_f32_32x32x16_bf16 v[50:65], v[72:75], v[80:83], v[50:65]
	v_lshl_or_b32 v80, v66, 2, s18
	v_and_b32_e32 v66, 31, v68
	v_lshlrev_b32_e32 v66, 1, v66
	v_mov_b32_e32 v81, v67
	v_lshl_add_u64 v[68:69], v[70:71], 0, v[66:67]
	v_lshlrev_b64 v[70:71], 8, v[80:81]
	v_lshl_add_u64 v[70:71], v[68:69], 0, v[70:71]
	v_mfma_f32_32x32x16_bf16 v[2:17], v[76:79], v[88:91], v[2:17]
	v_or_b32_e32 v66, 1, v80
	s_waitcnt lgkmcnt(3)
	v_mfma_f32_32x32x16_bf16 v[50:65], v[84:87], v[104:107], v[50:65]
	v_mfma_f32_32x32x16_bf16 v[34:49], v[72:75], v[92:95], v[34:49]
	s_nop 10
	v_mfma_f32_32x32x16_bf16 v[18:33], v[72:75], v[96:99], v[18:33]
	v_mfma_f32_32x32x16_bf16 v[2:17], v[72:75], v[100:103], v[2:17]
	s_waitcnt lgkmcnt(2)
	v_mfma_f32_32x32x16_bf16 v[34:49], v[84:87], v[108:111], v[34:49]
	s_waitcnt lgkmcnt(1)
	v_mfma_f32_32x32x16_bf16 v[18:33], v[84:87], v[112:115], v[18:33]
	s_waitcnt lgkmcnt(0)
; __device__ __forceinline__ unsigned pk2(float lo, float hi) { f32x2 v = {lo, hi}; bf16x2_t b = __builtin_convertvector(v, bf16x2_t); return __builtin_bit_cast(unsigned, b); }
; __device__ __forceinline__ int crow(int r, int hi) { return (r & 3) + 8 * (r >> 2) + 4 * hi; }
; __device__ __forceinline__ void gla_inc_unit(Frame& F, int bh, int n) {
;     ...
;     bf16* sb = WSP(bf16, WS_SB) + (size_t)(bh * 64 + n) * 256 * 128;
; #pragma unroll
;     for (int c = 0; c < 4; ++c)
; #pragma unroll
;         for (int i = 0; i < 16; ++i) sb[(size_t)(32 * wid + crow(i, h)) * 128 + 32 * c + (lane & 31)] = (bf16)(pk2(acc[c][i], 0.f) & 0xffffu);
	v_mfma_f32_32x32x16_bf16 v[2:17], v[84:87], v[116:119], v[2:17]
	v_and_b32_e32 v82, 1, v0
	v_mov_b32_e32 v83, 0
	v_sub_u32_e32 v80, 0, v82
	v_mul_u32_u24_e32 v82, 0xfe, v82
	v_and_b32_e32 v80, 0x6060606, v80
	v_mov_b32_e32 v78, 0x1000
	v_mov_b32_e32 v79, 0
	v_lshl_add_u64 v[70:71], v[70:71], 0, v[82:83]
	v_xor_b32_e32 v80, 0x5040100, v80
	v_lshl_add_u64 v[76:77], v[70:71], 0, v[78:79]
	v_cvt_pk_bf16_f32 v88, v50, v51
	v_cvt_pk_bf16_f32 v89, v52, v53
	v_cvt_pk_bf16_f32 v90, v54, v55
	v_cvt_pk_bf16_f32 v91, v56, v57
	v_mov_b32_dpp v92, v88 quad_perm:[1,0,3,2] row_mask:0xf bank_mask:0xf
	v_mov_b32_dpp v93, v89 quad_perm:[1,0,3,2] row_mask:0xf bank_mask:0xf
	v_mov_b32_dpp v94, v90 quad_perm:[1,0,3,2] row_mask:0xf bank_mask:0xf
	v_mov_b32_dpp v95, v91 quad_perm:[1,0,3,2] row_mask:0xf bank_mask:0xf
	v_perm_b32 v96, v92, v88, v80
	v_perm_b32 v97, v93, v89, v80
	v_perm_b32 v98, v94, v90, v80
	v_perm_b32 v99, v95, v91, v80
	global_store_dword v[70:71], v96, off
	global_store_dword v[70:71], v97, off offset:512
	global_store_dword v[70:71], v98, off offset:2048
	global_store_dword v[70:71], v99, off offset:2560
	v_cvt_pk_bf16_f32 v88, v58, v59
	v_cvt_pk_bf16_f32 v89, v60, v61
	v_cvt_pk_bf16_f32 v90, v62, v63
	v_cvt_pk_bf16_f32 v91, v64, v65
	v_mov_b32_dpp v92, v88 quad_perm:[1,0,3,2] row_mask:0xf bank_mask:0xf
	v_mov_b32_dpp v93, v89 quad_perm:[1,0,3,2] row_mask:0xf bank_mask:0xf
	v_mov_b32_dpp v94, v90 quad_perm:[1,0,3,2] row_mask:0xf bank_mask:0xf
	v_mov_b32_dpp v95, v91 quad_perm:[1,0,3,2] row_mask:0xf bank_mask:0xf
	v_perm_b32 v96, v92, v88, v80
	v_perm_b32 v97, v93, v89, v80
	v_perm_b32 v98, v94, v90, v80
	v_perm_b32 v99, v95, v91, v80
	global_store_dword v[76:77], v96, off
	global_store_dword v[76:77], v97, off offset:512
	global_store_dword v[76:77], v98, off offset:2048
	global_store_dword v[76:77], v99, off offset:2560
	v_cvt_pk_bf16_f32 v88, v34, v35
	v_cvt_pk_bf16_f32 v89, v36, v37
	v_cvt_pk_bf16_f32 v90, v38, v39
	v_cvt_pk_bf16_f32 v91, v40, v41
	v_mov_b32_dpp v92, v88 quad_perm:[1,0,3,2] row_mask:0xf bank_mask:0xf
	v_mov_b32_dpp v93, v89 quad_perm:[1,0,3,2] row_mask:0xf bank_mask:0xf
	v_mov_b32_dpp v94, v90 quad_perm:[1,0,3,2] row_mask:0xf bank_mask:0xf
	v_mov_b32_dpp v95, v91 quad_perm:[1,0,3,2] row_mask:0xf bank_mask:0xf
	v_perm_b32 v96, v92, v88, v80
	v_perm_b32 v97, v93, v89, v80
	v_perm_b32 v98, v94, v90, v80
	v_perm_b32 v99, v95, v91, v80
	global_store_dword v[70:71], v96, off offset:64
	global_store_dword v[70:71], v97, off offset:576
	global_store_dword v[70:71], v98, off offset:2112
	global_store_dword v[70:71], v99, off offset:2624
	v_cvt_pk_bf16_f32 v88, v42, v43
	v_cvt_pk_bf16_f32 v89, v44, v45
	v_cvt_pk_bf16_f32 v90, v46, v47
	v_cvt_pk_bf16_f32 v91, v48, v49
	v_mov_b32_dpp v92, v88 quad_perm:[1,0,3,2] row_mask:0xf bank_mask:0xf
	v_mov_b32_dpp v93, v89 quad_perm:[1,0,3,2] row_mask:0xf bank_mask:0xf
	v_mov_b32_dpp v94, v90 quad_perm:[1,0,3,2] row_mask:0xf bank_mask:0xf
	v_mov_b32_dpp v95, v91 quad_perm:[1,0,3,2] row_mask:0xf bank_mask:0xf
	v_perm_b32 v96, v92, v88, v80
	v_perm_b32 v97, v93, v89, v80
	v_perm_b32 v98, v94, v90, v80
	v_perm_b32 v99, v95, v91, v80
	global_store_dword v[76:77], v96, off offset:64
	global_store_dword v[76:77], v97, off offset:576
	global_store_dword v[76:77], v98, off offset:2112
	global_store_dword v[76:77], v99, off offset:2624
	v_cvt_pk_bf16_f32 v88, v18, v19
	v_cvt_pk_bf16_f32 v89, v20, v21
	v_cvt_pk_bf16_f32 v90, v22, v23
	v_cvt_pk_bf16_f32 v91, v24, v25
	v_mov_b32_dpp v92, v88 quad_perm:[1,0,3,2] row_mask:0xf bank_mask:0xf
	v_mov_b32_dpp v93, v89 quad_perm:[1,0,3,2] row_mask:0xf bank_mask:0xf
	v_mov_b32_dpp v94, v90 quad_perm:[1,0,3,2] row_mask:0xf bank_mask:0xf
	v_mov_b32_dpp v95, v91 quad_perm:[1,0,3,2] row_mask:0xf bank_mask:0xf
	v_perm_b32 v96, v92, v88, v80
	v_perm_b32 v97, v93, v89, v80
	v_perm_b32 v98, v94, v90, v80
	v_perm_b32 v99, v95, v91, v80
	global_store_dword v[70:71], v96, off offset:128
	global_store_dword v[70:71], v97, off offset:640
	global_store_dword v[70:71], v98, off offset:2176
	global_store_dword v[70:71], v99, off offset:2688
	v_cvt_pk_bf16_f32 v88, v26, v27
	v_cvt_pk_bf16_f32 v89, v28, v29
	v_cvt_pk_bf16_f32 v90, v30, v31
	v_cvt_pk_bf16_f32 v91, v32, v33
	v_mov_b32_dpp v92, v88 quad_perm:[1,0,3,2] row_mask:0xf bank_mask:0xf
	v_mov_b32_dpp v93, v89 quad_perm:[1,0,3,2] row_mask:0xf bank_mask:0xf
	v_mov_b32_dpp v94, v90 quad_perm:[1,0,3,2] row_mask:0xf bank_mask:0xf
	v_mov_b32_dpp v95, v91 quad_perm:[1,0,3,2] row_mask:0xf bank_mask:0xf
	v_perm_b32 v96, v92, v88, v80
	v_perm_b32 v97, v93, v89, v80
	v_perm_b32 v98, v94, v90, v80
	v_perm_b32 v99, v95, v91, v80
	global_store_dword v[76:77], v96, off offset:128
	global_store_dword v[76:77], v97, off offset:640
	global_store_dword v[76:77], v98, off offset:2176
	global_store_dword v[76:77], v99, off offset:2688
	v_cvt_pk_bf16_f32 v88, v2, v3
	v_cvt_pk_bf16_f32 v89, v4, v5
	v_cvt_pk_bf16_f32 v90, v6, v7
	v_cvt_pk_bf16_f32 v91, v8, v9
	v_mov_b32_dpp v92, v88 quad_perm:[1,0,3,2] row_mask:0xf bank_mask:0xf
	v_mov_b32_dpp v93, v89 quad_perm:[1,0,3,2] row_mask:0xf bank_mask:0xf
	v_mov_b32_dpp v94, v90 quad_perm:[1,0,3,2] row_mask:0xf bank_mask:0xf
	v_mov_b32_dpp v95, v91 quad_perm:[1,0,3,2] row_mask:0xf bank_mask:0xf
	v_perm_b32 v96, v92, v88, v80
	v_perm_b32 v97, v93, v89, v80
	v_perm_b32 v98, v94, v90, v80
	v_perm_b32 v99, v95, v91, v80
	global_store_dword v[70:71], v96, off offset:192
	global_store_dword v[70:71], v97, off offset:704
	global_store_dword v[70:71], v98, off offset:2240
	global_store_dword v[70:71], v99, off offset:2752
	v_cvt_pk_bf16_f32 v88, v10, v11
	v_cvt_pk_bf16_f32 v89, v12, v13
	v_cvt_pk_bf16_f32 v90, v14, v15
	v_cvt_pk_bf16_f32 v91, v16, v17
	v_mov_b32_dpp v92, v88 quad_perm:[1,0,3,2] row_mask:0xf bank_mask:0xf
	v_mov_b32_dpp v93, v89 quad_perm:[1,0,3,2] row_mask:0xf bank_mask:0xf
	v_mov_b32_dpp v94, v90 quad_perm:[1,0,3,2] row_mask:0xf bank_mask:0xf
	v_mov_b32_dpp v95, v91 quad_perm:[1,0,3,2] row_mask:0xf bank_mask:0xf
	v_perm_b32 v96, v92, v88, v80
	v_perm_b32 v97, v93, v89, v80
	v_perm_b32 v98, v94, v90, v80
	v_perm_b32 v99, v95, v91, v80
	global_store_dword v[76:77], v96, off offset:192
	global_store_dword v[76:77], v97, off offset:704
	global_store_dword v[76:77], v98, off offset:2240
	global_store_dword v[76:77], v99, off offset:2752
	s_waitcnt vmcnt(63) expcnt(7) lgkmcnt(15)
	s_barrier
	s_cbranch_scc1 .LBB0_645
